# final_candidate_A_with_dtype_comment_and_grid_guards
# baseline (speedup 1.0000x reference)
; #define PG8_LAS __attribute__((address_space(3)))
; DEVI int obid() { int t = blockIdx.x; asm volatile("" : "+s"(t)); return t; }
;     __device__ __forceinline__ bool next(int i, Unit& u) const { if (i != 0 || c >= n) return false; u.pm = pm; u.pn = c & 3; return true; }
;     __host__ __device__ bool next(int i, Unit& u) const {
;         const long L = (long)i * G + c; if (L >= nwg) return false;
;         int wgid = (int)L; { const int q = nwg / NXCD, r = nwg % NXCD, xcd = wgid % NXCD, off = wgid / NXCD; wgid = (xcd < r ? xcd * (q + 1) : r * (q + 1) + (xcd - r) * q) + off; }
;         const int nig = WGM * nN, gid = wgid / nig, fm = gid * WGM, gsz = (nM - fm) < WGM ? (nM - fm) : WGM;
;         u.pm = fm + ((wgid % nig) % gsz); u.pn = (wgid % nig) / gsz; return true;
; template <class Epi>
; __device__ __forceinline__ void run_gemm(unsigned char* smem, const bf16_t* A, int lda, const bf16_t* Bt, int N, int K, const Epi& E) {
;   pg8::Gemm g{A, Bt, MP, N, K, lda, K};
;   pg8::StaticOrder S; S.init(MP, N, (int)gridDim.x, obid());
;   pg8::gemm_phase<Epi, pg8::StaticOrder, true, true>((PG8_LAS unsigned char*)smem, g, S, E);
.LBB0_1453:
	v_readlane_b32 s35, v254, 22
	s_cmp_lg_u32 s52, 0x100
	s_cbranch_scc1 .Lrebal_skip1
	s_sub_i32 s35, 0xff, s35
.Lrebal_skip1:
	v_mov_b32_e32 v0, v128
	s_cmpk_lt_i32 s35, 0x204
	v_readlane_b32 s72, v255, 8
	s_cselect_b64 s[0:1], -1, 0
	s_cmpk_gt_i32 s35, 0x203
	v_readfirstlane_b32 s8, v0
	v_readlane_b32 s73, v255, 9
	s_cbranch_scc1 .LBB0_1459
	s_ashr_i32 s2, s35, 31
	s_lshr_b32 s2, s2, 29
	s_add_i32 s4, s35, s2
	s_and_b32 s2, s4, -8
	s_sub_i32 s5, s35, s2
	s_cmp_gt_i32 s5, 3
	s_mov_b64 s[2:3], -1
	s_cbranch_scc0 .LBB0_1456
	s_lshl_b32 s2, s5, 6
	s_or_b32 s6, s2, 4
	s_mov_b64 s[2:3], 0

; DEVI int obid() { int t = blockIdx.x; asm volatile("" : "+s"(t)); return t; }
; __global__ void __launch_bounds__(NT, 2) fwd_megakernel(Params p) {
;     ...
;       for (int it = obid(); it < 64; it += gridDim.x) fcum_item(p, smem, it);
.LBB0_1577:
	v_readlane_b32 s8, v254, 22
	s_cmp_lg_u32 s52, 0x100
	s_cbranch_scc1 .Lrebal_skip2
	s_sub_i32 s8, s8, 0x83
.Lrebal_skip2:
	s_cmp_gt_u32 s8, 63
	s_cbranch_scc0 .LBB0_1582
